# first X-pass K/V tile loads issued before the last exchange reads and barrier
# baseline (speedup 1.0000x reference)
; DI void attn_a_x(unsigned char* ws, LAS unsigned char* buf, int bh, int ra, int i0, int lane) {
;     ...
;     const int qpa = ra + 16 * (i0 + r), qpb = qpa + 8;
;     const float m0 = ((const float*)(ws + WS_GAINS))[400];
;     QT a, b; qt_init(a, Q + (size_t)qpa * 64, h); qt_init(b, Q + (size_t)qpb * 64, h);
;     {
;         const float* exa = (const float*)(ws + WS_EXO) + ((size_t)bh * SEQ + qpa) * 64 + 4 * h;
;         const float* exb = exa + 8 * 64;
; #pragma unroll
;         for (int g = 0; g < 4; ++g) {
;             const f32x4 a0 = *(const f32x4*)(exa + 8 * g), a1 = *(const f32x4*)(exa + 32 + 8 * g), b0 = *(const f32x4*)(exb + 8 * g), b1 = *(const f32x4*)(exb + 32 + 8 * g);
; #pragma unroll
;             for (int j = 0; j < 4; ++j) { a.st.o0[4 * g + j] = a0[j]; a.st.o1[4 * g + j] = a1[j]; b.st.o0[4 * g + j] = b0[j]; b.st.o1[4 * g + j] = b1[j]; }
;         }
;         const float* exl = (const float*)(ws + WS_EXL) + (size_t)bh * SEQ;
;         a.st.l = (h == 0) ? exl[qpa] : 0.f; b.st.l = (h == 0) ? exl[qpb] : 0.f;
;     }
.LBB0_603:
	s_lshl_b32 s16, s56, 5
	v_or_b32_e32 v0, s16, v214
	v_lshlrev_b32_e32 v81, 4, v0
	v_add_u32_e32 v186, s22, v81
	v_ashrrev_i32_e32 v187, 31, v186
	v_add_u32_e32 v188, 8, v186
	v_ashrrev_i32_e32 v189, 31, v188
	s_waitcnt lgkmcnt(0)
	global_load_dword v80, v183, s[68:69]
	v_mov_b32_e32 v203, v68
	v_mov_b32_e32 v48, v144
	v_mov_b32_e32 v49, v145
	v_mov_b32_e32 v50, v146
	v_mov_b32_e32 v51, v147
	v_mov_b32_e32 v52, v148
	v_mov_b32_e32 v53, v149
	v_mov_b32_e32 v54, v150
	v_mov_b32_e32 v55, v151
	v_mov_b32_e32 v56, v152
	v_mov_b32_e32 v57, v153
	v_mov_b32_e32 v58, v154
	v_mov_b32_e32 v59, v155
	v_mov_b32_e32 v60, v156
	v_mov_b32_e32 v61, v157
	v_mov_b32_e32 v62, v158
	v_mov_b32_e32 v63, v159
	v_mov_b32_e32 v32, v160
	v_mov_b32_e32 v33, v161
	v_mov_b32_e32 v34, v162
	v_mov_b32_e32 v35, v163
	v_mov_b32_e32 v36, v164
	v_mov_b32_e32 v37, v165
	v_mov_b32_e32 v38, v166
	v_mov_b32_e32 v39, v167
	v_mov_b32_e32 v40, v168
	v_mov_b32_e32 v41, v169
	v_mov_b32_e32 v42, v170
	v_mov_b32_e32 v43, v171
	v_mov_b32_e32 v44, v172
	v_mov_b32_e32 v45, v173
	v_mov_b32_e32 v46, v174
	v_mov_b32_e32 v47, v175
	s_cmp_gt_u32 s56, 3
	s_mov_b32 s63, 0
	s_cbranch_scc1 .LBB0_610

; DI int a_next(int tau, int ra, int i0) { int t = tau + 1, kb, ks, hi, who; while (t < 18 && !a_tile_desc(t, ra, i0, kb, ks, hi, who)) ++t; return t; }
; DI void tile_gload(TileRegs& t, const bf16_t* K, const bf16_t* V, int kbase, int kstride, int lane) {
;     const int row0 = lane >> 3, ch = lane & 7;
; #pragma unroll
;     for (int i = 0; i < 4; ++i) {
;         const unsigned off = (unsigned)((kbase + kstride * (row0 + 8 * i)) * 128 + ch * 16);
;         t.k[i] = *(const u32x4*)((const unsigned char*)K + off); t.v[i] = *(const u32x4*)((const unsigned char*)V + off);
;     }
; DI void attn_a_x(unsigned char* ws, LAS unsigned char* buf, int bh, int ra, int i0, int lane) {
;     ...
;     int tc = a_next(-1, ra, i0);
;     { int kb, ks, hi, who; (void)a_tile_desc(tc, ra, i0, kb, ks, hi, who); tile_gload(tr, K, V, kb, ks, lane); }
.LBB0_610:
	s_add_i32 s8, s16, 0xffffff80
	s_lshl_b32 s6, s8, 4
	s_add_i32 s6, s6, s22
	s_lshl_b32 s7, s63, 16
	s_lshl_b32 s14, s6, 7
	s_add_i32 s7, s7, s14
	v_add_u32_e32 v64, s7, v181
	global_load_dwordx4 v[172:175], v64, s[12:13]
	global_load_dwordx4 v[168:171], v64, s[10:11]
	v_add_u32_e32 v64, s7, v193
	global_load_dwordx4 v[164:167], v64, s[12:13]
	global_load_dwordx4 v[160:163], v64, s[10:11]
	v_add_u32_e32 v64, s7, v194
	global_load_dwordx4 v[156:159], v64, s[12:13]
	global_load_dwordx4 v[152:155], v64, s[10:11]
	v_add_u32_e32 v64, s7, v195
	global_load_dwordx4 v[148:151], v64, s[12:13]
	global_load_dwordx4 v[144:147], v64, s[10:11]
	s_add_i32 s14, s57, 0xfffff900
	s_lshl_b32 s15, s56, 7
	s_or_b32 s16, s14, s23
	v_add_u32_e32 v82, s6, v196
	s_mov_b32 s17, s63
	ds_read_b128 v[16:19], v67 offset:0
	ds_read_b128 v[20:23], v67 offset:32
	ds_read_b128 v[24:27], v67 offset:64
	ds_read_b128 v[28:31], v67 offset:96
	ds_read_b128 v[0:3], v67 offset:128
	ds_read_b128 v[4:7], v67 offset:160
	ds_read_b128 v[8:11], v67 offset:192
	ds_read_b128 v[12:15], v67 offset:224
	ds_read_b128 v[136:139], v73
	ds_read_b128 v[128:131], v74
	ds_read_b128 v[124:127], v75
	ds_read_b128 v[112:115], v76
	ds_read_b128 v[140:143], v73 offset:4608
	ds_read_b128 v[132:135], v74 offset:4608
	ds_read_b128 v[120:123], v75 offset:4608
	ds_read_b128 v[116:119], v76 offset:4608
	v_mov_b32_e32 v202, 0
	s_mov_b32 exec_hi, 0
	ds_read_b32 v202, v67 offset:256
	s_mov_b64 exec, -1
	s_waitcnt lgkmcnt(0)
	s_barrier
